# P3|P4 grid barrier replaced by seam: scan-done counter (64 scan workgroups, with L2 write-back) + own panel team counter
# baseline (speedup 1.0000x reference)
; __device__ __forceinline__ unsigned xb_ld(unsigned* p)              { return __hip_atomic_load(p, __ATOMIC_RELAXED, __HIP_MEMORY_SCOPE_AGENT); }
; __device__ __forceinline__ unsigned xb_add(unsigned* p, unsigned v) { return __hip_atomic_fetch_add(p, v, __ATOMIC_RELAXED, __HIP_MEMORY_SCOPE_AGENT); }
; #define XB_SPIN(cond, bar) do { unsigned _sp = 0; while (cond) { __builtin_amdgcn_s_sleep(1); \
;     if ((++_sp & 255u) == 0u) { if (xb_ld(&(bar)[XB_TMO])) break; if (_sp > XB_SPIN_CAP) { atomicAdd(&(bar)[XB_TMO], 1u); break; } } } } while (0)
; #define BOTH(k) (IN(k) && (k) + 1 < hi)
; #define GRID_BAR() xcd_barrier(bar)
; __device__ __forceinline__ void xcd_barrier(const XcdBarrier& b) {
;     asm volatile("s_waitcnt vmcnt(0)" ::: "memory");
;     __syncthreads();
;     if (threadIdx.x == 0) {
;         unsigned* bar = b.bar;
;         __builtin_amdgcn_s_waitcnt(0);
;         unsigned nloc = b.st[0], nx = b.st[1];
;         if (nloc == 0u) { xcd_barrier_complete(bar, b.x, nloc, nx); b.st[0] = nloc; b.st[1] = nx; }
;         const unsigned old = xb_add(&bar[XB_XSUB(b.x)], 1u);
;         asm volatile("buffer_inv sc1" ::: "memory");
;         const unsigned gen = old / nloc;
;         if (old + 1u == (gen + 1u) * nloc) {
;             __builtin_amdgcn_fence(__ATOMIC_RELEASE, "agent");
;             asm volatile("s_waitcnt vmcnt(0)" ::: "memory");
;             const unsigned og = xb_add(&bar[XB_TOP], 1u);
;             const unsigned tg = og / nx;
;             if (og + 1u == (tg + 1u) * nx) xb_add(&bar[XB_TOPGEN], 1u);
;             else XB_SPIN(xb_ld(&bar[XB_TOPGEN]) == tg, bar);
;             asm volatile("" ::: "memory");
;             xb_add(&bar[XB_XGEN(b.x)], 1u);
;             asm volatile("s_waitcnt vmcnt(0)" ::: "memory");
;         } else {
;             XB_SPIN(xb_ld(&bar[XB_XGEN(b.x)]) == gen, bar);
;             asm volatile("s_waitcnt vmcnt(0)" ::: "memory");
;         }
;     }
;     __syncthreads();
; __global__ void __launch_bounds__(NWAVES * 64, 2) fwd(Args args) {
;     ...
;         if (BOTH(3)) GRID_BAR();
.LBB0_841:
	s_and_saveexec_b64 s[0:1], s[96:97]
	s_cbranch_execz .Lts3_a
	s_and_b32 s4, s2, 63
	s_lshl_b32 s4, s4, 2
	s_add_u32 s10, s60, s4
	s_addc_u32 s11, s61, 0
	v_mov_b32_e32 v1, 0x28000
	global_load_dword v2, v1, s[10:11] sc1
	global_load_dword v3, v1, s[10:11] offset:256 sc1
	global_load_dword v4, v1, s[10:11] offset:512 sc1
	global_load_dword v5, v1, s[10:11] offset:768 sc1
.Lts3_a:
	s_or_b64 exec, exec, s[0:1]
	s_waitcnt vmcnt(0)
	s_barrier
	s_and_saveexec_b64 s[0:1], s[96:97]
	s_cbranch_execz .LBB0_889
	s_add_i32 s4, s90, 1
	v_xor_b32_e32 v2, s4, v2
	v_xor_b32_e32 v3, s4, v3
	v_xor_b32_e32 v4, s4, v4
	v_xor_b32_e32 v5, s4, v5
	v_or3_b32 v2, v2, v3, v4
	v_or_b32_e32 v2, v2, v5
	v_cmp_ne_u32_e32 vcc, 0, v2
	s_cmpk_lt_u32 s2, 64
	s_cselect_b64 s[10:11], -1, 0
	s_or_b64 vcc, vcc, s[10:11]
	s_cbranch_vccz .Lts3_nowb
	buffer_wbl2 sc1
	s_waitcnt vmcnt(0)
.Lts3_nowb:
	s_and_b32 s3, s2, 7
	s_lshl_b32 s3, s3, 3
	s_bfe_u32 s4, s2, 0x30003
	s_or_b32 s3, s3, s4
	s_lshl_b32 s3, s3, 6
	s_add_u32 s8, s60, s3
	s_addc_u32 s9, s61, 0
	s_add_u32 s8, s8, 0x2f000
	s_addc_u32 s9, s9, 0
	v_mov_b32_e32 v1, 0
	v_mov_b32_e32 v2, 1
	v_mov_b32_e32 v3, 0x2c200
	v_mov_b32_e32 v5, 0
	global_atomic_add v1, v2, s[8:9]
	s_cmpk_gt_u32 s2, 63
	s_cbranch_scc1 .Lts3_spin
	global_atomic_add v3, v2, s[60:61]
.Lts3_spin:
	global_load_dword v6, v1, s[8:9] sc1
	global_load_dword v7, v3, s[60:61] sc1
	s_waitcnt vmcnt(0)
	v_lshrrev_b32_e32 v6, 2, v6
	v_lshrrev_b32_e32 v7, 6, v7
	v_min_u32_e32 v6, v6, v7
	v_cmp_ne_u32_e32 vcc, 0, v6
	s_cbranch_vccnz .Lts3_done
	s_sleep 1
	v_add_u32_e32 v5, 1, v5
	v_cmp_gt_u32_e32 vcc, 0x4000, v5
	s_cbranch_vccnz .Lts3_spin
	global_atomic_add v1, v2, s[58:59] offset:512
.Lts3_done:
	buffer_inv sc1
	s_waitcnt vmcnt(0)
.LBB0_889:
	s_or_b64 exec, exec, s[0:1]
	s_waitcnt lgkmcnt(0)
	s_barrier
